# P0 phase_mod nt loads plus nt on three once-per-unit attention Q fragment loads
# speedup vs baseline: 1.0127x; 1.0127x over previous
.LBB0_670:
	s_waitcnt vmcnt(3)
	v_mfma_f32_32x32x16_bf16 v[80:95], v[124:127], v[108:111], 0
	s_waitcnt vmcnt(2)
	v_mfma_f32_32x32x16_bf16 v[80:95], v[120:123], v[104:107], v[80:95]
	global_load_dwordx4 v[128:131], v[172:173], off
	global_load_dwordx4 v[124:127], v[174:175], off
	global_load_dwordx4 v[120:123], v[176:177], off
	global_load_dwordx4 v[108:111], v[178:179], off
	global_load_dwordx4 v[104:107], v[180:181], off nt
	global_load_dwordx4 v[10:13], v[182:183], off
	global_load_dwordx4 v[6:9], v[184:185], off
	global_load_dwordx4 v[2:5], v[186:187], off
	s_waitcnt vmcnt(9)
	v_mfma_f32_32x32x16_bf16 v[80:95], v[116:119], v[100:103], v[80:95]
	s_waitcnt vmcnt(8)
	v_mfma_f32_32x32x16_bf16 v[80:95], v[112:115], v[96:99], v[80:95]
	s_nop 11
	v_max_f32_e32 v0, v81, v81
	v_max_f32_e32 v14, v80, v80
	v_max_f32_e32 v0, v14, v0
	v_max_f32_e32 v14, v83, v83
	v_max_f32_e32 v15, v82, v82
	v_max_f32_e32 v14, v15, v14
	v_max_f32_e32 v15, v87, v87
	v_max_f32_e32 v96, v86, v86
	v_max_f32_e32 v15, v96, v15
	v_max3_f32 v15, v84, v85, v15
	v_max3_f32 v0, v0, v14, v15
	v_max_f32_e32 v14, v91, v91
	v_max_f32_e32 v15, v90, v90
	v_max_f32_e32 v14, v15, v14
	v_max_f32_e32 v15, v95, v95
	v_max_f32_e32 v96, v94, v94
	v_max_f32_e32 v15, v96, v15
	v_max3_f32 v14, v88, v89, v14
	v_max3_f32 v15, v92, v93, v15
	v_max3_f32 v0, v0, v14, v15
	v_mov_b32_e32 v14, v0
	s_nop 1
	v_permlane32_swap_b32_e32 v0, v14
	s_waitcnt lgkmcnt(0)
	v_max_f32_e32 v14, v14, v14
	v_max_f32_e32 v0, v0, v14
	v_cmp_gt_f32_e32 vcc, v0, v192
	s_cbranch_vccz .LBB0_672
	v_max_f32_e32 v0, v0, v0
	v_max_f32_e32 v14, v192, v192
	v_max_f32_e32 v14, v14, v0
	v_sub_f32_e32 v0, v192, v14
	v_exp_f32_e32 v0, v0
	v_mov_b32_e32 v192, v14
	v_mul_f32_e32 v191, v191, v0
	v_pk_mul_f32 v[78:79], v[78:79], v[0:1] op_sel_hi:[1,0]
	v_pk_mul_f32 v[76:77], v[76:77], v[0:1] op_sel_hi:[1,0]
	v_pk_mul_f32 v[74:75], v[74:75], v[0:1] op_sel_hi:[1,0]
	v_pk_mul_f32 v[72:73], v[72:73], v[0:1] op_sel_hi:[1,0]
	v_pk_mul_f32 v[70:71], v[70:71], v[0:1] op_sel_hi:[1,0]
	v_pk_mul_f32 v[68:69], v[68:69], v[0:1] op_sel_hi:[1,0]
	v_pk_mul_f32 v[66:67], v[66:67], v[0:1] op_sel_hi:[1,0]
	v_pk_mul_f32 v[64:65], v[64:65], v[0:1] op_sel_hi:[1,0]
	v_pk_mul_f32 v[62:63], v[62:63], v[0:1] op_sel_hi:[1,0]
	v_pk_mul_f32 v[60:61], v[60:61], v[0:1] op_sel_hi:[1,0]
	v_pk_mul_f32 v[58:59], v[58:59], v[0:1] op_sel_hi:[1,0]
	v_pk_mul_f32 v[56:57], v[56:57], v[0:1] op_sel_hi:[1,0]
	v_pk_mul_f32 v[54:55], v[54:55], v[0:1] op_sel_hi:[1,0]
	v_pk_mul_f32 v[52:53], v[52:53], v[0:1] op_sel_hi:[1,0]
	v_pk_mul_f32 v[50:51], v[50:51], v[0:1] op_sel_hi:[1,0]
	v_pk_mul_f32 v[48:49], v[48:49], v[0:1] op_sel_hi:[1,0]
	v_pk_mul_f32 v[46:47], v[46:47], v[0:1] op_sel_hi:[1,0]
	v_pk_mul_f32 v[44:45], v[44:45], v[0:1] op_sel_hi:[1,0]
	v_pk_mul_f32 v[42:43], v[42:43], v[0:1] op_sel_hi:[1,0]
	v_pk_mul_f32 v[40:41], v[40:41], v[0:1] op_sel_hi:[1,0]
	v_pk_mul_f32 v[38:39], v[38:39], v[0:1] op_sel_hi:[1,0]
	v_pk_mul_f32 v[36:37], v[36:37], v[0:1] op_sel_hi:[1,0]
	v_pk_mul_f32 v[34:35], v[34:35], v[0:1] op_sel_hi:[1,0]
	v_pk_mul_f32 v[32:33], v[32:33], v[0:1] op_sel_hi:[1,0]
	v_pk_mul_f32 v[30:31], v[30:31], v[0:1] op_sel_hi:[1,0]
	v_pk_mul_f32 v[28:29], v[28:29], v[0:1] op_sel_hi:[1,0]
	v_pk_mul_f32 v[26:27], v[26:27], v[0:1] op_sel_hi:[1,0]
	v_pk_mul_f32 v[24:25], v[24:25], v[0:1] op_sel_hi:[1,0]
	v_pk_mul_f32 v[22:23], v[22:23], v[0:1] op_sel_hi:[1,0]
	v_pk_mul_f32 v[20:21], v[20:21], v[0:1] op_sel_hi:[1,0]
	v_pk_mul_f32 v[18:19], v[18:19], v[0:1] op_sel_hi:[1,0]
	v_pk_mul_f32 v[16:17], v[16:17], v[0:1] op_sel_hi:[1,0]

.LBB0_687:
	s_waitcnt vmcnt(3)
	v_mfma_f32_32x32x16_bf16 v[80:95], v[124:127], v[108:111], 0
	s_waitcnt vmcnt(2)
	v_mfma_f32_32x32x16_bf16 v[80:95], v[120:123], v[104:107], v[80:95]
	global_load_dwordx4 v[132:135], v[176:177], off
	global_load_dwordx4 v[124:127], v[178:179], off
	global_load_dwordx4 v[120:123], v[180:181], off nt
	global_load_dwordx4 v[10:13], v[182:183], off
	global_load_dwordx4 v[2:5], v[184:185], off
	global_load_dwordx4 v[6:9], v[186:187], off
	s_waitcnt vmcnt(7)
	v_mfma_f32_32x32x16_bf16 v[80:95], v[116:119], v[100:103], v[80:95]
	global_load_dwordx4 v[116:119], v[188:189], off
	global_load_dwordx4 v[128:131], v[190:191], off
	s_waitcnt vmcnt(8)
	v_mfma_f32_32x32x16_bf16 v[80:95], v[112:115], v[96:99], v[80:95]
	s_nop 11
	v_max_f32_e32 v0, v81, v81
	v_max_f32_e32 v14, v80, v80
	v_max_f32_e32 v0, v14, v0
	v_max_f32_e32 v14, v83, v83
	v_max_f32_e32 v15, v82, v82
	v_max_f32_e32 v14, v15, v14
	v_max_f32_e32 v15, v87, v87
	v_max_f32_e32 v112, v86, v86
	v_max_f32_e32 v15, v112, v15
	v_max3_f32 v15, v84, v85, v15
	v_max3_f32 v0, v0, v14, v15
	v_max_f32_e32 v14, v91, v91
	v_max_f32_e32 v15, v90, v90
	v_max_f32_e32 v14, v15, v14
	v_max_f32_e32 v15, v95, v95
	v_max_f32_e32 v112, v94, v94
	v_max_f32_e32 v15, v112, v15
	v_max3_f32 v14, v88, v89, v14
	v_max3_f32 v15, v92, v93, v15
	v_max3_f32 v0, v0, v14, v15
	v_mov_b32_e32 v14, v0
	s_nop 1
	v_permlane32_swap_b32_e32 v0, v14
	s_waitcnt lgkmcnt(0)
	v_max_f32_e32 v14, v14, v14
	v_max_f32_e32 v0, v0, v14
	v_cmp_gt_f32_e32 vcc, v0, v171
	s_cbranch_vccz .LBB0_689
	v_max_f32_e32 v0, v0, v0
	v_max_f32_e32 v14, v171, v171
	v_max_f32_e32 v14, v14, v0
	v_sub_f32_e32 v0, v171, v14
	v_exp_f32_e32 v0, v0
	v_mov_b32_e32 v171, v14
	v_mul_f32_e32 v218, v218, v0
	v_pk_mul_f32 v[78:79], v[78:79], v[0:1] op_sel_hi:[1,0]
	v_pk_mul_f32 v[76:77], v[76:77], v[0:1] op_sel_hi:[1,0]
	v_pk_mul_f32 v[74:75], v[74:75], v[0:1] op_sel_hi:[1,0]
	v_pk_mul_f32 v[72:73], v[72:73], v[0:1] op_sel_hi:[1,0]
	v_pk_mul_f32 v[70:71], v[70:71], v[0:1] op_sel_hi:[1,0]
	v_pk_mul_f32 v[68:69], v[68:69], v[0:1] op_sel_hi:[1,0]
	v_pk_mul_f32 v[66:67], v[66:67], v[0:1] op_sel_hi:[1,0]
	v_pk_mul_f32 v[64:65], v[64:65], v[0:1] op_sel_hi:[1,0]
	v_pk_mul_f32 v[62:63], v[62:63], v[0:1] op_sel_hi:[1,0]
	v_pk_mul_f32 v[60:61], v[60:61], v[0:1] op_sel_hi:[1,0]
	v_pk_mul_f32 v[58:59], v[58:59], v[0:1] op_sel_hi:[1,0]
	v_pk_mul_f32 v[56:57], v[56:57], v[0:1] op_sel_hi:[1,0]
	v_pk_mul_f32 v[54:55], v[54:55], v[0:1] op_sel_hi:[1,0]
	v_pk_mul_f32 v[52:53], v[52:53], v[0:1] op_sel_hi:[1,0]
	v_pk_mul_f32 v[50:51], v[50:51], v[0:1] op_sel_hi:[1,0]
	v_pk_mul_f32 v[48:49], v[48:49], v[0:1] op_sel_hi:[1,0]
	v_pk_mul_f32 v[46:47], v[46:47], v[0:1] op_sel_hi:[1,0]
	v_pk_mul_f32 v[44:45], v[44:45], v[0:1] op_sel_hi:[1,0]
	v_pk_mul_f32 v[42:43], v[42:43], v[0:1] op_sel_hi:[1,0]
	v_pk_mul_f32 v[40:41], v[40:41], v[0:1] op_sel_hi:[1,0]
	v_pk_mul_f32 v[38:39], v[38:39], v[0:1] op_sel_hi:[1,0]
	v_pk_mul_f32 v[36:37], v[36:37], v[0:1] op_sel_hi:[1,0]
	v_pk_mul_f32 v[34:35], v[34:35], v[0:1] op_sel_hi:[1,0]
	v_pk_mul_f32 v[32:33], v[32:33], v[0:1] op_sel_hi:[1,0]
	v_pk_mul_f32 v[30:31], v[30:31], v[0:1] op_sel_hi:[1,0]
	v_pk_mul_f32 v[28:29], v[28:29], v[0:1] op_sel_hi:[1,0]
	v_pk_mul_f32 v[26:27], v[26:27], v[0:1] op_sel_hi:[1,0]
	v_pk_mul_f32 v[24:25], v[24:25], v[0:1] op_sel_hi:[1,0]
	v_pk_mul_f32 v[22:23], v[22:23], v[0:1] op_sel_hi:[1,0]
	v_pk_mul_f32 v[20:21], v[20:21], v[0:1] op_sel_hi:[1,0]
	v_pk_mul_f32 v[18:19], v[18:19], v[0:1] op_sel_hi:[1,0]
	v_pk_mul_f32 v[16:17], v[16:17], v[0:1] op_sel_hi:[1,0]

.LBB0_715:
	s_waitcnt vmcnt(3)
	v_mfma_f32_32x32x16_bf16 v[80:95], v[112:115], v[108:111], 0
	s_waitcnt vmcnt(2)
	v_mfma_f32_32x32x16_bf16 v[80:95], v[10:13], v[104:107], v[80:95]
	global_load_dwordx4 v[124:127], v[172:173], off
	global_load_dwordx4 v[120:123], v[174:175], off
	global_load_dwordx4 v[116:119], v[176:177], off
	global_load_dwordx4 v[112:115], v[178:179], off
	global_load_dwordx4 v[108:111], v[180:181], off nt
	global_load_dwordx4 v[104:107], v[182:183], off
	s_waitcnt vmcnt(7)
	v_mfma_f32_32x32x16_bf16 v[80:95], v[6:9], v[100:103], v[80:95]
	global_load_dwordx4 v[10:13], v[184:185], off
	global_load_dwordx4 v[6:9], v[186:187], off
	s_waitcnt vmcnt(8)
	v_mfma_f32_32x32x16_bf16 v[80:95], v[2:5], v[96:99], v[80:95]
	s_nop 11
	v_max_f32_e32 v2, v81, v81
	v_max_f32_e32 v3, v80, v80
	v_max_f32_e32 v2, v3, v2
	v_max_f32_e32 v3, v83, v83
	v_max_f32_e32 v4, v82, v82
	v_max_f32_e32 v3, v4, v3
	v_max_f32_e32 v4, v87, v87
	v_max_f32_e32 v5, v86, v86
	v_max_f32_e32 v4, v5, v4
	v_max3_f32 v4, v84, v85, v4
	v_max3_f32 v2, v2, v3, v4
	v_max_f32_e32 v3, v91, v91
	v_max_f32_e32 v4, v90, v90
	v_max_f32_e32 v3, v4, v3
	v_max_f32_e32 v4, v95, v95
	v_max_f32_e32 v5, v94, v94
	v_max_f32_e32 v4, v5, v4
	v_max3_f32 v3, v88, v89, v3
	v_max3_f32 v4, v92, v93, v4
	v_max3_f32 v2, v2, v3, v4
	v_mov_b32_e32 v3, v2
	s_nop 1
	v_permlane32_swap_b32_e32 v2, v3
	s_waitcnt lgkmcnt(0)
	v_max_f32_e32 v3, v3, v3
	v_max_f32_e32 v2, v2, v3
	v_cmp_gt_f32_e32 vcc, v2, v208
	s_cbranch_vccz .LBB0_717
	v_max_f32_e32 v2, v2, v2
	v_max_f32_e32 v3, v208, v208
	v_max_f32_e32 v3, v3, v2
	v_sub_f32_e32 v2, v208, v3
	v_exp_f32_e32 v2, v2
	v_mov_b32_e32 v208, v3
	v_mul_f32_e32 v0, v0, v2
	v_pk_mul_f32 v[78:79], v[78:79], v[2:3] op_sel_hi:[1,0]
	v_pk_mul_f32 v[76:77], v[76:77], v[2:3] op_sel_hi:[1,0]
	v_pk_mul_f32 v[74:75], v[74:75], v[2:3] op_sel_hi:[1,0]
	v_pk_mul_f32 v[72:73], v[72:73], v[2:3] op_sel_hi:[1,0]
	v_pk_mul_f32 v[70:71], v[70:71], v[2:3] op_sel_hi:[1,0]
	v_pk_mul_f32 v[68:69], v[68:69], v[2:3] op_sel_hi:[1,0]
	v_pk_mul_f32 v[66:67], v[66:67], v[2:3] op_sel_hi:[1,0]
	v_pk_mul_f32 v[64:65], v[64:65], v[2:3] op_sel_hi:[1,0]
	v_pk_mul_f32 v[62:63], v[62:63], v[2:3] op_sel_hi:[1,0]
	v_pk_mul_f32 v[60:61], v[60:61], v[2:3] op_sel_hi:[1,0]
	v_pk_mul_f32 v[58:59], v[58:59], v[2:3] op_sel_hi:[1,0]
	v_pk_mul_f32 v[56:57], v[56:57], v[2:3] op_sel_hi:[1,0]
	v_pk_mul_f32 v[54:55], v[54:55], v[2:3] op_sel_hi:[1,0]
	v_pk_mul_f32 v[52:53], v[52:53], v[2:3] op_sel_hi:[1,0]
	v_pk_mul_f32 v[50:51], v[50:51], v[2:3] op_sel_hi:[1,0]
	v_pk_mul_f32 v[48:49], v[48:49], v[2:3] op_sel_hi:[1,0]
	v_pk_mul_f32 v[46:47], v[46:47], v[2:3] op_sel_hi:[1,0]
	v_pk_mul_f32 v[44:45], v[44:45], v[2:3] op_sel_hi:[1,0]
	v_pk_mul_f32 v[42:43], v[42:43], v[2:3] op_sel_hi:[1,0]
	v_pk_mul_f32 v[40:41], v[40:41], v[2:3] op_sel_hi:[1,0]
	v_pk_mul_f32 v[38:39], v[38:39], v[2:3] op_sel_hi:[1,0]
	v_pk_mul_f32 v[36:37], v[36:37], v[2:3] op_sel_hi:[1,0]
	v_pk_mul_f32 v[34:35], v[34:35], v[2:3] op_sel_hi:[1,0]
	v_pk_mul_f32 v[32:33], v[32:33], v[2:3] op_sel_hi:[1,0]
	v_pk_mul_f32 v[30:31], v[30:31], v[2:3] op_sel_hi:[1,0]
	v_pk_mul_f32 v[28:29], v[28:29], v[2:3] op_sel_hi:[1,0]
	v_pk_mul_f32 v[26:27], v[26:27], v[2:3] op_sel_hi:[1,0]
	v_pk_mul_f32 v[24:25], v[24:25], v[2:3] op_sel_hi:[1,0]
	v_pk_mul_f32 v[22:23], v[22:23], v[2:3] op_sel_hi:[1,0]
	v_pk_mul_f32 v[20:21], v[20:21], v[2:3] op_sel_hi:[1,0]
	v_pk_mul_f32 v[18:19], v[18:19], v[2:3] op_sel_hi:[1,0]
	v_pk_mul_f32 v[16:17], v[16:17], v[2:3] op_sel_hi:[1,0]

.LBB0_959:
	s_mul_hi_i32 s0, s3, 0x2aaaaaab
	s_lshr_b32 s1, s0, 31
	s_ashr_i32 s4, s0, 3
	s_add_i32 s4, s4, s1
	s_mul_i32 s0, s4, 48
	s_sub_i32 s0, s3, s0
	s_lshl_b32 s0, s0, 7
	s_ashr_i32 s1, s0, 31
	s_mul_i32 s6, s4, 0x1800000
	s_lshl_b64 s[0:1], s[0:1], 2
	s_mul_hi_i32 s5, s4, 0x1800000
	s_add_u32 s6, s6, s0
	s_addc_u32 s7, s5, s1
	s_waitcnt vmcnt(0)
	v_mov_b32_e32 v26, 0
	v_lshl_add_u64 v[44:45], v[42:43], 0, s[6:7]
	s_mov_b64 s[6:7], 0
	v_mov_b32_e32 v46, v39
	v_mov_b32_e32 v27, v26
	v_mov_b32_e32 v28, v26
	v_mov_b32_e32 v29, v26
	v_mov_b32_e32 v30, v26
	v_mov_b32_e32 v31, v26
	v_mov_b32_e32 v32, v26
	v_mov_b32_e32 v33, v26
	v_mov_b32_e32 v34, v26
	v_mov_b32_e32 v35, v26
	v_mov_b32_e32 v36, v26
	v_mov_b32_e32 v37, v26
	s_mov_b64 s[40:41], 0x6000
	v_mov_b64_e32 v[180:181], v[44:45]
	ds_read_b128 v[2:5], v46
	ds_read_b128 v[6:9], v46 offset:16
	ds_read_b128 v[10:13], v46 offset:4096
	ds_read_b128 v[14:17], v46 offset:4112
	ds_read_b128 v[18:21], v46 offset:8192
	ds_read_b128 v[22:25], v46 offset:8208
	global_load_dwordx4 v[100:103], v[180:181], off nt
	v_lshl_add_u64 v[180:181], s[40:41], 0, v[180:181]
	global_load_dwordx4 v[104:107], v[180:181], off nt
	v_lshl_add_u64 v[180:181], s[40:41], 0, v[180:181]
	global_load_dwordx4 v[108:111], v[180:181], off nt
	v_lshl_add_u64 v[180:181], s[40:41], 0, v[180:181]
	global_load_dwordx4 v[112:115], v[180:181], off nt
	v_lshl_add_u64 v[180:181], s[40:41], 0, v[180:181]
	global_load_dwordx4 v[116:119], v[180:181], off nt
	v_lshl_add_u64 v[180:181], s[40:41], 0, v[180:181]
	global_load_dwordx4 v[120:123], v[180:181], off nt
	v_lshl_add_u64 v[180:181], s[40:41], 0, v[180:181]
	global_load_dwordx4 v[124:127], v[180:181], off nt
	v_lshl_add_u64 v[180:181], s[40:41], 0, v[180:181]
	global_load_dwordx4 v[128:131], v[180:181], off nt
	v_lshl_add_u64 v[180:181], s[40:41], 0, v[180:181]
	global_load_dwordx4 v[132:135], v[180:181], off nt
	v_lshl_add_u64 v[180:181], s[40:41], 0, v[180:181]
	global_load_dwordx4 v[136:139], v[180:181], off nt
	v_lshl_add_u64 v[180:181], s[40:41], 0, v[180:181]
	global_load_dwordx4 v[140:143], v[180:181], off nt
	v_lshl_add_u64 v[180:181], s[40:41], 0, v[180:181]
	global_load_dwordx4 v[144:147], v[180:181], off nt
	v_lshl_add_u64 v[180:181], s[40:41], 0, v[180:181]
	global_load_dwordx4 v[148:151], v[180:181], off nt
	v_lshl_add_u64 v[180:181], s[40:41], 0, v[180:181]
	global_load_dwordx4 v[152:155], v[180:181], off nt
	v_lshl_add_u64 v[180:181], s[40:41], 0, v[180:181]
	global_load_dwordx4 v[156:159], v[180:181], off nt
	v_lshl_add_u64 v[180:181], s[40:41], 0, v[180:181]
	global_load_dwordx4 v[160:163], v[180:181], off nt
	v_lshl_add_u64 v[180:181], s[40:41], 0, v[180:181]
	global_load_dwordx4 v[164:167], v[180:181], off nt
	v_lshl_add_u64 v[180:181], s[40:41], 0, v[180:181]
	global_load_dwordx4 v[168:171], v[180:181], off nt
	v_lshl_add_u64 v[180:181], s[40:41], 0, v[180:181]
	global_load_dwordx4 v[172:175], v[180:181], off nt
	v_lshl_add_u64 v[180:181], s[40:41], 0, v[180:181]
	global_load_dwordx4 v[176:179], v[180:181], off nt
	v_lshl_add_u64 v[180:181], s[40:41], 0, v[180:181]
	ds_read_b128 v[50:53], v46 offset:32
	ds_read_b128 v[54:57], v46 offset:48
	ds_read_b128 v[58:61], v46 offset:4128
	ds_read_b128 v[62:65], v46 offset:4144
	ds_read_b128 v[66:69], v46 offset:8224
	ds_read_b128 v[70:73], v46 offset:8240
	s_waitcnt lgkmcnt(6)
	s_waitcnt vmcnt(19)
	v_pk_fma_f32 v[26:27], v[100:101], v[2:3], v[26:27] op_sel_hi:[1,0,1]
	v_pk_fma_f32 v[28:29], v[102:103], v[2:3], v[28:29] op_sel_hi:[1,0,1]
	v_pk_fma_f32 v[30:31], v[100:101], v[10:11], v[30:31] op_sel_hi:[1,0,1]
	v_pk_fma_f32 v[32:33], v[102:103], v[10:11], v[32:33] op_sel_hi:[1,0,1]
	v_pk_fma_f32 v[34:35], v[100:101], v[18:19], v[34:35] op_sel_hi:[1,0,1]
	v_pk_fma_f32 v[36:37], v[102:103], v[18:19], v[36:37] op_sel_hi:[1,0,1]
	global_load_dwordx4 v[100:103], v[180:181], off nt
	v_lshl_add_u64 v[180:181], s[40:41], 0, v[180:181]
	s_waitcnt vmcnt(19)
	v_pk_fma_f32 v[26:27], v[104:105], v[2:3], v[26:27] op_sel:[0,1,0]
	v_pk_fma_f32 v[28:29], v[106:107], v[2:3], v[28:29] op_sel:[0,1,0]
	v_pk_fma_f32 v[30:31], v[104:105], v[10:11], v[30:31] op_sel:[0,1,0]
	v_pk_fma_f32 v[32:33], v[106:107], v[10:11], v[32:33] op_sel:[0,1,0]
	v_pk_fma_f32 v[34:35], v[104:105], v[18:19], v[34:35] op_sel:[0,1,0]
	v_pk_fma_f32 v[36:37], v[106:107], v[18:19], v[36:37] op_sel:[0,1,0]
	global_load_dwordx4 v[104:107], v[180:181], off nt
	v_lshl_add_u64 v[180:181], s[40:41], 0, v[180:181]
	s_waitcnt vmcnt(19)
	v_pk_fma_f32 v[26:27], v[108:109], v[4:5], v[26:27] op_sel_hi:[1,0,1]
	v_pk_fma_f32 v[28:29], v[110:111], v[4:5], v[28:29] op_sel_hi:[1,0,1]
	v_pk_fma_f32 v[30:31], v[108:109], v[12:13], v[30:31] op_sel_hi:[1,0,1]
	v_pk_fma_f32 v[32:33], v[110:111], v[12:13], v[32:33] op_sel_hi:[1,0,1]
	v_pk_fma_f32 v[34:35], v[108:109], v[20:21], v[34:35] op_sel_hi:[1,0,1]
	v_pk_fma_f32 v[36:37], v[110:111], v[20:21], v[36:37] op_sel_hi:[1,0,1]
	global_load_dwordx4 v[108:111], v[180:181], off nt
	v_lshl_add_u64 v[180:181], s[40:41], 0, v[180:181]
	s_waitcnt vmcnt(19)
	v_pk_fma_f32 v[26:27], v[112:113], v[4:5], v[26:27] op_sel:[0,1,0]
	v_pk_fma_f32 v[28:29], v[114:115], v[4:5], v[28:29] op_sel:[0,1,0]
	v_pk_fma_f32 v[30:31], v[112:113], v[12:13], v[30:31] op_sel:[0,1,0]
	v_pk_fma_f32 v[32:33], v[114:115], v[12:13], v[32:33] op_sel:[0,1,0]
	v_pk_fma_f32 v[34:35], v[112:113], v[20:21], v[34:35] op_sel:[0,1,0]
	v_pk_fma_f32 v[36:37], v[114:115], v[20:21], v[36:37] op_sel:[0,1,0]
	global_load_dwordx4 v[112:115], v[180:181], off nt
	v_lshl_add_u64 v[180:181], s[40:41], 0, v[180:181]
	s_waitcnt vmcnt(19)
	v_pk_fma_f32 v[26:27], v[116:117], v[6:7], v[26:27] op_sel_hi:[1,0,1]
	v_pk_fma_f32 v[28:29], v[118:119], v[6:7], v[28:29] op_sel_hi:[1,0,1]
	v_pk_fma_f32 v[30:31], v[116:117], v[14:15], v[30:31] op_sel_hi:[1,0,1]
	v_pk_fma_f32 v[32:33], v[118:119], v[14:15], v[32:33] op_sel_hi:[1,0,1]
	v_pk_fma_f32 v[34:35], v[116:117], v[22:23], v[34:35] op_sel_hi:[1,0,1]
	v_pk_fma_f32 v[36:37], v[118:119], v[22:23], v[36:37] op_sel_hi:[1,0,1]
	global_load_dwordx4 v[116:119], v[180:181], off nt
	v_lshl_add_u64 v[180:181], s[40:41], 0, v[180:181]
	s_waitcnt vmcnt(19)
	v_pk_fma_f32 v[26:27], v[120:121], v[6:7], v[26:27] op_sel:[0,1,0]
	v_pk_fma_f32 v[28:29], v[122:123], v[6:7], v[28:29] op_sel:[0,1,0]
	v_pk_fma_f32 v[30:31], v[120:121], v[14:15], v[30:31] op_sel:[0,1,0]
	v_pk_fma_f32 v[32:33], v[122:123], v[14:15], v[32:33] op_sel:[0,1,0]
	v_pk_fma_f32 v[34:35], v[120:121], v[22:23], v[34:35] op_sel:[0,1,0]
	v_pk_fma_f32 v[36:37], v[122:123], v[22:23], v[36:37] op_sel:[0,1,0]
	global_load_dwordx4 v[120:123], v[180:181], off nt
	v_lshl_add_u64 v[180:181], s[40:41], 0, v[180:181]
	s_waitcnt vmcnt(19)
	v_pk_fma_f32 v[26:27], v[124:125], v[8:9], v[26:27] op_sel_hi:[1,0,1]
	v_pk_fma_f32 v[28:29], v[126:127], v[8:9], v[28:29] op_sel_hi:[1,0,1]
	v_pk_fma_f32 v[30:31], v[124:125], v[16:17], v[30:31] op_sel_hi:[1,0,1]
	v_pk_fma_f32 v[32:33], v[126:127], v[16:17], v[32:33] op_sel_hi:[1,0,1]
	v_pk_fma_f32 v[34:35], v[124:125], v[24:25], v[34:35] op_sel_hi:[1,0,1]
	v_pk_fma_f32 v[36:37], v[126:127], v[24:25], v[36:37] op_sel_hi:[1,0,1]
	global_load_dwordx4 v[124:127], v[180:181], off nt
	v_lshl_add_u64 v[180:181], s[40:41], 0, v[180:181]
	s_waitcnt vmcnt(19)
	v_pk_fma_f32 v[26:27], v[128:129], v[8:9], v[26:27] op_sel:[0,1,0]
	v_pk_fma_f32 v[28:29], v[130:131], v[8:9], v[28:29] op_sel:[0,1,0]
	v_pk_fma_f32 v[30:31], v[128:129], v[16:17], v[30:31] op_sel:[0,1,0]
	v_pk_fma_f32 v[32:33], v[130:131], v[16:17], v[32:33] op_sel:[0,1,0]
	v_pk_fma_f32 v[34:35], v[128:129], v[24:25], v[34:35] op_sel:[0,1,0]
	v_pk_fma_f32 v[36:37], v[130:131], v[24:25], v[36:37] op_sel:[0,1,0]
	global_load_dwordx4 v[128:131], v[180:181], off nt
	v_lshl_add_u64 v[180:181], s[40:41], 0, v[180:181]
	ds_read_b128 v[2:5], v46 offset:64
	ds_read_b128 v[6:9], v46 offset:80
	ds_read_b128 v[10:13], v46 offset:4160
	ds_read_b128 v[14:17], v46 offset:4176
	ds_read_b128 v[18:21], v46 offset:8256
	ds_read_b128 v[22:25], v46 offset:8272
	s_waitcnt lgkmcnt(6)
	s_waitcnt vmcnt(19)
	v_pk_fma_f32 v[26:27], v[132:133], v[50:51], v[26:27] op_sel_hi:[1,0,1]
	v_pk_fma_f32 v[28:29], v[134:135], v[50:51], v[28:29] op_sel_hi:[1,0,1]
	v_pk_fma_f32 v[30:31], v[132:133], v[58:59], v[30:31] op_sel_hi:[1,0,1]
	v_pk_fma_f32 v[32:33], v[134:135], v[58:59], v[32:33] op_sel_hi:[1,0,1]
	v_pk_fma_f32 v[34:35], v[132:133], v[66:67], v[34:35] op_sel_hi:[1,0,1]
	v_pk_fma_f32 v[36:37], v[134:135], v[66:67], v[36:37] op_sel_hi:[1,0,1]
	global_load_dwordx4 v[132:135], v[180:181], off nt
	v_lshl_add_u64 v[180:181], s[40:41], 0, v[180:181]
	s_waitcnt vmcnt(19)
	v_pk_fma_f32 v[26:27], v[136:137], v[50:51], v[26:27] op_sel:[0,1,0]
	v_pk_fma_f32 v[28:29], v[138:139], v[50:51], v[28:29] op_sel:[0,1,0]
	v_pk_fma_f32 v[30:31], v[136:137], v[58:59], v[30:31] op_sel:[0,1,0]
	v_pk_fma_f32 v[32:33], v[138:139], v[58:59], v[32:33] op_sel:[0,1,0]
	v_pk_fma_f32 v[34:35], v[136:137], v[66:67], v[34:35] op_sel:[0,1,0]
	v_pk_fma_f32 v[36:37], v[138:139], v[66:67], v[36:37] op_sel:[0,1,0]
	global_load_dwordx4 v[136:139], v[180:181], off nt
	v_lshl_add_u64 v[180:181], s[40:41], 0, v[180:181]
	s_waitcnt vmcnt(19)
	v_pk_fma_f32 v[26:27], v[140:141], v[52:53], v[26:27] op_sel_hi:[1,0,1]
	v_pk_fma_f32 v[28:29], v[142:143], v[52:53], v[28:29] op_sel_hi:[1,0,1]
	v_pk_fma_f32 v[30:31], v[140:141], v[60:61], v[30:31] op_sel_hi:[1,0,1]
	v_pk_fma_f32 v[32:33], v[142:143], v[60:61], v[32:33] op_sel_hi:[1,0,1]
	v_pk_fma_f32 v[34:35], v[140:141], v[68:69], v[34:35] op_sel_hi:[1,0,1]
	v_pk_fma_f32 v[36:37], v[142:143], v[68:69], v[36:37] op_sel_hi:[1,0,1]
	global_load_dwordx4 v[140:143], v[180:181], off nt
	v_lshl_add_u64 v[180:181], s[40:41], 0, v[180:181]
	s_waitcnt vmcnt(19)
	v_pk_fma_f32 v[26:27], v[144:145], v[52:53], v[26:27] op_sel:[0,1,0]
	v_pk_fma_f32 v[28:29], v[146:147], v[52:53], v[28:29] op_sel:[0,1,0]
	v_pk_fma_f32 v[30:31], v[144:145], v[60:61], v[30:31] op_sel:[0,1,0]
	v_pk_fma_f32 v[32:33], v[146:147], v[60:61], v[32:33] op_sel:[0,1,0]
	v_pk_fma_f32 v[34:35], v[144:145], v[68:69], v[34:35] op_sel:[0,1,0]
	v_pk_fma_f32 v[36:37], v[146:147], v[68:69], v[36:37] op_sel:[0,1,0]
	global_load_dwordx4 v[144:147], v[180:181], off nt
	v_lshl_add_u64 v[180:181], s[40:41], 0, v[180:181]
	s_waitcnt vmcnt(19)
	v_pk_fma_f32 v[26:27], v[148:149], v[54:55], v[26:27] op_sel_hi:[1,0,1]
	v_pk_fma_f32 v[28:29], v[150:151], v[54:55], v[28:29] op_sel_hi:[1,0,1]
	v_pk_fma_f32 v[30:31], v[148:149], v[62:63], v[30:31] op_sel_hi:[1,0,1]
	v_pk_fma_f32 v[32:33], v[150:151], v[62:63], v[32:33] op_sel_hi:[1,0,1]
	v_pk_fma_f32 v[34:35], v[148:149], v[70:71], v[34:35] op_sel_hi:[1,0,1]
	v_pk_fma_f32 v[36:37], v[150:151], v[70:71], v[36:37] op_sel_hi:[1,0,1]
	global_load_dwordx4 v[148:151], v[180:181], off nt
	v_lshl_add_u64 v[180:181], s[40:41], 0, v[180:181]
	s_waitcnt vmcnt(19)
	v_pk_fma_f32 v[26:27], v[152:153], v[54:55], v[26:27] op_sel:[0,1,0]
	v_pk_fma_f32 v[28:29], v[154:155], v[54:55], v[28:29] op_sel:[0,1,0]
	v_pk_fma_f32 v[30:31], v[152:153], v[62:63], v[30:31] op_sel:[0,1,0]
	v_pk_fma_f32 v[32:33], v[154:155], v[62:63], v[32:33] op_sel:[0,1,0]
	v_pk_fma_f32 v[34:35], v[152:153], v[70:71], v[34:35] op_sel:[0,1,0]
	v_pk_fma_f32 v[36:37], v[154:155], v[70:71], v[36:37] op_sel:[0,1,0]
	global_load_dwordx4 v[152:155], v[180:181], off nt
	v_lshl_add_u64 v[180:181], s[40:41], 0, v[180:181]
	s_waitcnt vmcnt(19)
	v_pk_fma_f32 v[26:27], v[156:157], v[56:57], v[26:27] op_sel_hi:[1,0,1]
	v_pk_fma_f32 v[28:29], v[158:159], v[56:57], v[28:29] op_sel_hi:[1,0,1]
	v_pk_fma_f32 v[30:31], v[156:157], v[64:65], v[30:31] op_sel_hi:[1,0,1]
	v_pk_fma_f32 v[32:33], v[158:159], v[64:65], v[32:33] op_sel_hi:[1,0,1]
	v_pk_fma_f32 v[34:35], v[156:157], v[72:73], v[34:35] op_sel_hi:[1,0,1]
	v_pk_fma_f32 v[36:37], v[158:159], v[72:73], v[36:37] op_sel_hi:[1,0,1]
	global_load_dwordx4 v[156:159], v[180:181], off nt
	v_lshl_add_u64 v[180:181], s[40:41], 0, v[180:181]
	s_waitcnt vmcnt(19)
	v_pk_fma_f32 v[26:27], v[160:161], v[56:57], v[26:27] op_sel:[0,1,0]
	v_pk_fma_f32 v[28:29], v[162:163], v[56:57], v[28:29] op_sel:[0,1,0]
	v_pk_fma_f32 v[30:31], v[160:161], v[64:65], v[30:31] op_sel:[0,1,0]
	v_pk_fma_f32 v[32:33], v[162:163], v[64:65], v[32:33] op_sel:[0,1,0]
	v_pk_fma_f32 v[34:35], v[160:161], v[72:73], v[34:35] op_sel:[0,1,0]
	v_pk_fma_f32 v[36:37], v[162:163], v[72:73], v[36:37] op_sel:[0,1,0]
	global_load_dwordx4 v[160:163], v[180:181], off nt
	v_lshl_add_u64 v[180:181], s[40:41], 0, v[180:181]
	ds_read_b128 v[50:53], v46 offset:96
	ds_read_b128 v[54:57], v46 offset:112
	ds_read_b128 v[58:61], v46 offset:4192
	ds_read_b128 v[62:65], v46 offset:4208
	ds_read_b128 v[66:69], v46 offset:8288
	ds_read_b128 v[70:73], v46 offset:8304
	s_waitcnt lgkmcnt(6)
	s_waitcnt vmcnt(19)
	v_pk_fma_f32 v[26:27], v[164:165], v[2:3], v[26:27] op_sel_hi:[1,0,1]
	v_pk_fma_f32 v[28:29], v[166:167], v[2:3], v[28:29] op_sel_hi:[1,0,1]
	v_pk_fma_f32 v[30:31], v[164:165], v[10:11], v[30:31] op_sel_hi:[1,0,1]
	v_pk_fma_f32 v[32:33], v[166:167], v[10:11], v[32:33] op_sel_hi:[1,0,1]
	v_pk_fma_f32 v[34:35], v[164:165], v[18:19], v[34:35] op_sel_hi:[1,0,1]
	v_pk_fma_f32 v[36:37], v[166:167], v[18:19], v[36:37] op_sel_hi:[1,0,1]
	global_load_dwordx4 v[164:167], v[180:181], off nt
	v_lshl_add_u64 v[180:181], s[40:41], 0, v[180:181]
	s_waitcnt vmcnt(19)
	v_pk_fma_f32 v[26:27], v[168:169], v[2:3], v[26:27] op_sel:[0,1,0]
	v_pk_fma_f32 v[28:29], v[170:171], v[2:3], v[28:29] op_sel:[0,1,0]
	v_pk_fma_f32 v[30:31], v[168:169], v[10:11], v[30:31] op_sel:[0,1,0]
	v_pk_fma_f32 v[32:33], v[170:171], v[10:11], v[32:33] op_sel:[0,1,0]
	v_pk_fma_f32 v[34:35], v[168:169], v[18:19], v[34:35] op_sel:[0,1,0]
	v_pk_fma_f32 v[36:37], v[170:171], v[18:19], v[36:37] op_sel:[0,1,0]
	global_load_dwordx4 v[168:171], v[180:181], off nt
	v_lshl_add_u64 v[180:181], s[40:41], 0, v[180:181]
	s_waitcnt vmcnt(19)
	v_pk_fma_f32 v[26:27], v[172:173], v[4:5], v[26:27] op_sel_hi:[1,0,1]
	v_pk_fma_f32 v[28:29], v[174:175], v[4:5], v[28:29] op_sel_hi:[1,0,1]
	v_pk_fma_f32 v[30:31], v[172:173], v[12:13], v[30:31] op_sel_hi:[1,0,1]
	v_pk_fma_f32 v[32:33], v[174:175], v[12:13], v[32:33] op_sel_hi:[1,0,1]
	v_pk_fma_f32 v[34:35], v[172:173], v[20:21], v[34:35] op_sel_hi:[1,0,1]
	v_pk_fma_f32 v[36:37], v[174:175], v[20:21], v[36:37] op_sel_hi:[1,0,1]
	global_load_dwordx4 v[172:175], v[180:181], off nt
	v_lshl_add_u64 v[180:181], s[40:41], 0, v[180:181]
	s_waitcnt vmcnt(19)
	v_pk_fma_f32 v[26:27], v[176:177], v[4:5], v[26:27] op_sel:[0,1,0]
	v_pk_fma_f32 v[28:29], v[178:179], v[4:5], v[28:29] op_sel:[0,1,0]
	v_pk_fma_f32 v[30:31], v[176:177], v[12:13], v[30:31] op_sel:[0,1,0]
	v_pk_fma_f32 v[32:33], v[178:179], v[12:13], v[32:33] op_sel:[0,1,0]
	v_pk_fma_f32 v[34:35], v[176:177], v[20:21], v[34:35] op_sel:[0,1,0]
	v_pk_fma_f32 v[36:37], v[178:179], v[20:21], v[36:37] op_sel:[0,1,0]
	global_load_dwordx4 v[176:179], v[180:181], off nt
	v_lshl_add_u64 v[180:181], s[40:41], 0, v[180:181]
	s_waitcnt vmcnt(19)
	v_pk_fma_f32 v[26:27], v[100:101], v[6:7], v[26:27] op_sel_hi:[1,0,1]
	v_pk_fma_f32 v[28:29], v[102:103], v[6:7], v[28:29] op_sel_hi:[1,0,1]
	v_pk_fma_f32 v[30:31], v[100:101], v[14:15], v[30:31] op_sel_hi:[1,0,1]
	v_pk_fma_f32 v[32:33], v[102:103], v[14:15], v[32:33] op_sel_hi:[1,0,1]
	v_pk_fma_f32 v[34:35], v[100:101], v[22:23], v[34:35] op_sel_hi:[1,0,1]
	v_pk_fma_f32 v[36:37], v[102:103], v[22:23], v[36:37] op_sel_hi:[1,0,1]
	global_load_dwordx4 v[100:103], v[180:181], off nt
	v_lshl_add_u64 v[180:181], s[40:41], 0, v[180:181]
	s_waitcnt vmcnt(19)
	v_pk_fma_f32 v[26:27], v[104:105], v[6:7], v[26:27] op_sel:[0,1,0]
	v_pk_fma_f32 v[28:29], v[106:107], v[6:7], v[28:29] op_sel:[0,1,0]
	v_pk_fma_f32 v[30:31], v[104:105], v[14:15], v[30:31] op_sel:[0,1,0]
	v_pk_fma_f32 v[32:33], v[106:107], v[14:15], v[32:33] op_sel:[0,1,0]
	v_pk_fma_f32 v[34:35], v[104:105], v[22:23], v[34:35] op_sel:[0,1,0]
	v_pk_fma_f32 v[36:37], v[106:107], v[22:23], v[36:37] op_sel:[0,1,0]
	global_load_dwordx4 v[104:107], v[180:181], off nt
	v_lshl_add_u64 v[180:181], s[40:41], 0, v[180:181]
	s_waitcnt vmcnt(19)
	v_pk_fma_f32 v[26:27], v[108:109], v[8:9], v[26:27] op_sel_hi:[1,0,1]
	v_pk_fma_f32 v[28:29], v[110:111], v[8:9], v[28:29] op_sel_hi:[1,0,1]
	v_pk_fma_f32 v[30:31], v[108:109], v[16:17], v[30:31] op_sel_hi:[1,0,1]
	v_pk_fma_f32 v[32:33], v[110:111], v[16:17], v[32:33] op_sel_hi:[1,0,1]
	v_pk_fma_f32 v[34:35], v[108:109], v[24:25], v[34:35] op_sel_hi:[1,0,1]
	v_pk_fma_f32 v[36:37], v[110:111], v[24:25], v[36:37] op_sel_hi:[1,0,1]
	global_load_dwordx4 v[108:111], v[180:181], off nt
	v_lshl_add_u64 v[180:181], s[40:41], 0, v[180:181]
	s_waitcnt vmcnt(19)
	v_pk_fma_f32 v[26:27], v[112:113], v[8:9], v[26:27] op_sel:[0,1,0]
	v_pk_fma_f32 v[28:29], v[114:115], v[8:9], v[28:29] op_sel:[0,1,0]
	v_pk_fma_f32 v[30:31], v[112:113], v[16:17], v[30:31] op_sel:[0,1,0]
	v_pk_fma_f32 v[32:33], v[114:115], v[16:17], v[32:33] op_sel:[0,1,0]
	v_pk_fma_f32 v[34:35], v[112:113], v[24:25], v[34:35] op_sel:[0,1,0]
	v_pk_fma_f32 v[36:37], v[114:115], v[24:25], v[36:37] op_sel:[0,1,0]
	global_load_dwordx4 v[112:115], v[180:181], off nt
	v_lshl_add_u64 v[180:181], s[40:41], 0, v[180:181]
	ds_read_b128 v[2:5], v46 offset:128
	ds_read_b128 v[6:9], v46 offset:144
	ds_read_b128 v[10:13], v46 offset:4224
	ds_read_b128 v[14:17], v46 offset:4240
	ds_read_b128 v[18:21], v46 offset:8320
	ds_read_b128 v[22:25], v46 offset:8336
	s_waitcnt lgkmcnt(6)
	s_waitcnt vmcnt(19)
	v_pk_fma_f32 v[26:27], v[116:117], v[50:51], v[26:27] op_sel_hi:[1,0,1]
	v_pk_fma_f32 v[28:29], v[118:119], v[50:51], v[28:29] op_sel_hi:[1,0,1]
	v_pk_fma_f32 v[30:31], v[116:117], v[58:59], v[30:31] op_sel_hi:[1,0,1]
	v_pk_fma_f32 v[32:33], v[118:119], v[58:59], v[32:33] op_sel_hi:[1,0,1]
	v_pk_fma_f32 v[34:35], v[116:117], v[66:67], v[34:35] op_sel_hi:[1,0,1]
	v_pk_fma_f32 v[36:37], v[118:119], v[66:67], v[36:37] op_sel_hi:[1,0,1]
	global_load_dwordx4 v[116:119], v[180:181], off nt
	v_lshl_add_u64 v[180:181], s[40:41], 0, v[180:181]
	s_waitcnt vmcnt(19)
	v_pk_fma_f32 v[26:27], v[120:121], v[50:51], v[26:27] op_sel:[0,1,0]
	v_pk_fma_f32 v[28:29], v[122:123], v[50:51], v[28:29] op_sel:[0,1,0]
	v_pk_fma_f32 v[30:31], v[120:121], v[58:59], v[30:31] op_sel:[0,1,0]
	v_pk_fma_f32 v[32:33], v[122:123], v[58:59], v[32:33] op_sel:[0,1,0]
	v_pk_fma_f32 v[34:35], v[120:121], v[66:67], v[34:35] op_sel:[0,1,0]
	v_pk_fma_f32 v[36:37], v[122:123], v[66:67], v[36:37] op_sel:[0,1,0]
	global_load_dwordx4 v[120:123], v[180:181], off nt
	v_lshl_add_u64 v[180:181], s[40:41], 0, v[180:181]
	s_waitcnt vmcnt(19)
	v_pk_fma_f32 v[26:27], v[124:125], v[52:53], v[26:27] op_sel_hi:[1,0,1]
	v_pk_fma_f32 v[28:29], v[126:127], v[52:53], v[28:29] op_sel_hi:[1,0,1]
	v_pk_fma_f32 v[30:31], v[124:125], v[60:61], v[30:31] op_sel_hi:[1,0,1]
	v_pk_fma_f32 v[32:33], v[126:127], v[60:61], v[32:33] op_sel_hi:[1,0,1]
	v_pk_fma_f32 v[34:35], v[124:125], v[68:69], v[34:35] op_sel_hi:[1,0,1]
	v_pk_fma_f32 v[36:37], v[126:127], v[68:69], v[36:37] op_sel_hi:[1,0,1]
	global_load_dwordx4 v[124:127], v[180:181], off nt
	v_lshl_add_u64 v[180:181], s[40:41], 0, v[180:181]
	s_waitcnt vmcnt(19)
	v_pk_fma_f32 v[26:27], v[128:129], v[52:53], v[26:27] op_sel:[0,1,0]
	v_pk_fma_f32 v[28:29], v[130:131], v[52:53], v[28:29] op_sel:[0,1,0]
	v_pk_fma_f32 v[30:31], v[128:129], v[60:61], v[30:31] op_sel:[0,1,0]
	v_pk_fma_f32 v[32:33], v[130:131], v[60:61], v[32:33] op_sel:[0,1,0]
	v_pk_fma_f32 v[34:35], v[128:129], v[68:69], v[34:35] op_sel:[0,1,0]
	v_pk_fma_f32 v[36:37], v[130:131], v[68:69], v[36:37] op_sel:[0,1,0]
	global_load_dwordx4 v[128:131], v[180:181], off nt
	v_lshl_add_u64 v[180:181], s[40:41], 0, v[180:181]
	s_waitcnt vmcnt(19)
	v_pk_fma_f32 v[26:27], v[132:133], v[54:55], v[26:27] op_sel_hi:[1,0,1]
	v_pk_fma_f32 v[28:29], v[134:135], v[54:55], v[28:29] op_sel_hi:[1,0,1]
	v_pk_fma_f32 v[30:31], v[132:133], v[62:63], v[30:31] op_sel_hi:[1,0,1]
	v_pk_fma_f32 v[32:33], v[134:135], v[62:63], v[32:33] op_sel_hi:[1,0,1]
	v_pk_fma_f32 v[34:35], v[132:133], v[70:71], v[34:35] op_sel_hi:[1,0,1]
	v_pk_fma_f32 v[36:37], v[134:135], v[70:71], v[36:37] op_sel_hi:[1,0,1]
	global_load_dwordx4 v[132:135], v[180:181], off nt
	v_lshl_add_u64 v[180:181], s[40:41], 0, v[180:181]
	s_waitcnt vmcnt(19)
	v_pk_fma_f32 v[26:27], v[136:137], v[54:55], v[26:27] op_sel:[0,1,0]
	v_pk_fma_f32 v[28:29], v[138:139], v[54:55], v[28:29] op_sel:[0,1,0]
	v_pk_fma_f32 v[30:31], v[136:137], v[62:63], v[30:31] op_sel:[0,1,0]
	v_pk_fma_f32 v[32:33], v[138:139], v[62:63], v[32:33] op_sel:[0,1,0]
	v_pk_fma_f32 v[34:35], v[136:137], v[70:71], v[34:35] op_sel:[0,1,0]
	v_pk_fma_f32 v[36:37], v[138:139], v[70:71], v[36:37] op_sel:[0,1,0]
	global_load_dwordx4 v[136:139], v[180:181], off nt
	v_lshl_add_u64 v[180:181], s[40:41], 0, v[180:181]
	s_waitcnt vmcnt(19)
	v_pk_fma_f32 v[26:27], v[140:141], v[56:57], v[26:27] op_sel_hi:[1,0,1]
	v_pk_fma_f32 v[28:29], v[142:143], v[56:57], v[28:29] op_sel_hi:[1,0,1]
	v_pk_fma_f32 v[30:31], v[140:141], v[64:65], v[30:31] op_sel_hi:[1,0,1]
	v_pk_fma_f32 v[32:33], v[142:143], v[64:65], v[32:33] op_sel_hi:[1,0,1]
	v_pk_fma_f32 v[34:35], v[140:141], v[72:73], v[34:35] op_sel_hi:[1,0,1]
	v_pk_fma_f32 v[36:37], v[142:143], v[72:73], v[36:37] op_sel_hi:[1,0,1]
	global_load_dwordx4 v[140:143], v[180:181], off nt
	v_lshl_add_u64 v[180:181], s[40:41], 0, v[180:181]
	s_waitcnt vmcnt(19)
	v_pk_fma_f32 v[26:27], v[144:145], v[56:57], v[26:27] op_sel:[0,1,0]
	v_pk_fma_f32 v[28:29], v[146:147], v[56:57], v[28:29] op_sel:[0,1,0]
	v_pk_fma_f32 v[30:31], v[144:145], v[64:65], v[30:31] op_sel:[0,1,0]
	v_pk_fma_f32 v[32:33], v[146:147], v[64:65], v[32:33] op_sel:[0,1,0]
	v_pk_fma_f32 v[34:35], v[144:145], v[72:73], v[34:35] op_sel:[0,1,0]
	v_pk_fma_f32 v[36:37], v[146:147], v[72:73], v[36:37] op_sel:[0,1,0]
	global_load_dwordx4 v[144:147], v[180:181], off nt
	v_lshl_add_u64 v[180:181], s[40:41], 0, v[180:181]
	ds_read_b128 v[50:53], v46 offset:160
	ds_read_b128 v[54:57], v46 offset:176
	ds_read_b128 v[58:61], v46 offset:4256
	ds_read_b128 v[62:65], v46 offset:4272
	ds_read_b128 v[66:69], v46 offset:8352
	ds_read_b128 v[70:73], v46 offset:8368
	s_waitcnt lgkmcnt(6)
	s_waitcnt vmcnt(19)
	v_pk_fma_f32 v[26:27], v[148:149], v[2:3], v[26:27] op_sel_hi:[1,0,1]
	v_pk_fma_f32 v[28:29], v[150:151], v[2:3], v[28:29] op_sel_hi:[1,0,1]
	v_pk_fma_f32 v[30:31], v[148:149], v[10:11], v[30:31] op_sel_hi:[1,0,1]
	v_pk_fma_f32 v[32:33], v[150:151], v[10:11], v[32:33] op_sel_hi:[1,0,1]
	v_pk_fma_f32 v[34:35], v[148:149], v[18:19], v[34:35] op_sel_hi:[1,0,1]
	v_pk_fma_f32 v[36:37], v[150:151], v[18:19], v[36:37] op_sel_hi:[1,0,1]
	global_load_dwordx4 v[148:151], v[180:181], off nt
	v_lshl_add_u64 v[180:181], s[40:41], 0, v[180:181]
	s_waitcnt vmcnt(19)
	v_pk_fma_f32 v[26:27], v[152:153], v[2:3], v[26:27] op_sel:[0,1,0]
	v_pk_fma_f32 v[28:29], v[154:155], v[2:3], v[28:29] op_sel:[0,1,0]
	v_pk_fma_f32 v[30:31], v[152:153], v[10:11], v[30:31] op_sel:[0,1,0]
	v_pk_fma_f32 v[32:33], v[154:155], v[10:11], v[32:33] op_sel:[0,1,0]
	v_pk_fma_f32 v[34:35], v[152:153], v[18:19], v[34:35] op_sel:[0,1,0]
	v_pk_fma_f32 v[36:37], v[154:155], v[18:19], v[36:37] op_sel:[0,1,0]
	global_load_dwordx4 v[152:155], v[180:181], off nt
	v_lshl_add_u64 v[180:181], s[40:41], 0, v[180:181]
	s_waitcnt vmcnt(19)
	v_pk_fma_f32 v[26:27], v[156:157], v[4:5], v[26:27] op_sel_hi:[1,0,1]
	v_pk_fma_f32 v[28:29], v[158:159], v[4:5], v[28:29] op_sel_hi:[1,0,1]
	v_pk_fma_f32 v[30:31], v[156:157], v[12:13], v[30:31] op_sel_hi:[1,0,1]
	v_pk_fma_f32 v[32:33], v[158:159], v[12:13], v[32:33] op_sel_hi:[1,0,1]
	v_pk_fma_f32 v[34:35], v[156:157], v[20:21], v[34:35] op_sel_hi:[1,0,1]
	v_pk_fma_f32 v[36:37], v[158:159], v[20:21], v[36:37] op_sel_hi:[1,0,1]
	global_load_dwordx4 v[156:159], v[180:181], off nt
	v_lshl_add_u64 v[180:181], s[40:41], 0, v[180:181]
	s_waitcnt vmcnt(19)
	v_pk_fma_f32 v[26:27], v[160:161], v[4:5], v[26:27] op_sel:[0,1,0]
	v_pk_fma_f32 v[28:29], v[162:163], v[4:5], v[28:29] op_sel:[0,1,0]
	v_pk_fma_f32 v[30:31], v[160:161], v[12:13], v[30:31] op_sel:[0,1,0]
	v_pk_fma_f32 v[32:33], v[162:163], v[12:13], v[32:33] op_sel:[0,1,0]
	v_pk_fma_f32 v[34:35], v[160:161], v[20:21], v[34:35] op_sel:[0,1,0]
	v_pk_fma_f32 v[36:37], v[162:163], v[20:21], v[36:37] op_sel:[0,1,0]
	global_load_dwordx4 v[160:163], v[180:181], off nt
	v_lshl_add_u64 v[180:181], s[40:41], 0, v[180:181]
	s_waitcnt vmcnt(19)
	v_pk_fma_f32 v[26:27], v[164:165], v[6:7], v[26:27] op_sel_hi:[1,0,1]
	v_pk_fma_f32 v[28:29], v[166:167], v[6:7], v[28:29] op_sel_hi:[1,0,1]
	v_pk_fma_f32 v[30:31], v[164:165], v[14:15], v[30:31] op_sel_hi:[1,0,1]
	v_pk_fma_f32 v[32:33], v[166:167], v[14:15], v[32:33] op_sel_hi:[1,0,1]
	v_pk_fma_f32 v[34:35], v[164:165], v[22:23], v[34:35] op_sel_hi:[1,0,1]
	v_pk_fma_f32 v[36:37], v[166:167], v[22:23], v[36:37] op_sel_hi:[1,0,1]
	global_load_dwordx4 v[164:167], v[180:181], off nt
	v_lshl_add_u64 v[180:181], s[40:41], 0, v[180:181]
	s_waitcnt vmcnt(19)
	v_pk_fma_f32 v[26:27], v[168:169], v[6:7], v[26:27] op_sel:[0,1,0]
	v_pk_fma_f32 v[28:29], v[170:171], v[6:7], v[28:29] op_sel:[0,1,0]
	v_pk_fma_f32 v[30:31], v[168:169], v[14:15], v[30:31] op_sel:[0,1,0]
	v_pk_fma_f32 v[32:33], v[170:171], v[14:15], v[32:33] op_sel:[0,1,0]
	v_pk_fma_f32 v[34:35], v[168:169], v[22:23], v[34:35] op_sel:[0,1,0]
	v_pk_fma_f32 v[36:37], v[170:171], v[22:23], v[36:37] op_sel:[0,1,0]
	global_load_dwordx4 v[168:171], v[180:181], off nt
	v_lshl_add_u64 v[180:181], s[40:41], 0, v[180:181]
	s_waitcnt vmcnt(19)
	v_pk_fma_f32 v[26:27], v[172:173], v[8:9], v[26:27] op_sel_hi:[1,0,1]
	v_pk_fma_f32 v[28:29], v[174:175], v[8:9], v[28:29] op_sel_hi:[1,0,1]
	v_pk_fma_f32 v[30:31], v[172:173], v[16:17], v[30:31] op_sel_hi:[1,0,1]
	v_pk_fma_f32 v[32:33], v[174:175], v[16:17], v[32:33] op_sel_hi:[1,0,1]
	v_pk_fma_f32 v[34:35], v[172:173], v[24:25], v[34:35] op_sel_hi:[1,0,1]
	v_pk_fma_f32 v[36:37], v[174:175], v[24:25], v[36:37] op_sel_hi:[1,0,1]
	global_load_dwordx4 v[172:175], v[180:181], off nt
	v_lshl_add_u64 v[180:181], s[40:41], 0, v[180:181]
	s_waitcnt vmcnt(19)
	v_pk_fma_f32 v[26:27], v[176:177], v[8:9], v[26:27] op_sel:[0,1,0]
	v_pk_fma_f32 v[28:29], v[178:179], v[8:9], v[28:29] op_sel:[0,1,0]
	v_pk_fma_f32 v[30:31], v[176:177], v[16:17], v[30:31] op_sel:[0,1,0]
	v_pk_fma_f32 v[32:33], v[178:179], v[16:17], v[32:33] op_sel:[0,1,0]
	v_pk_fma_f32 v[34:35], v[176:177], v[24:25], v[34:35] op_sel:[0,1,0]
	v_pk_fma_f32 v[36:37], v[178:179], v[24:25], v[36:37] op_sel:[0,1,0]
	global_load_dwordx4 v[176:179], v[180:181], off nt
	v_lshl_add_u64 v[180:181], s[40:41], 0, v[180:181]
	ds_read_b128 v[2:5], v46 offset:192
	ds_read_b128 v[6:9], v46 offset:208
	ds_read_b128 v[10:13], v46 offset:4288
	ds_read_b128 v[14:17], v46 offset:4304
	ds_read_b128 v[18:21], v46 offset:8384
	ds_read_b128 v[22:25], v46 offset:8400
	s_waitcnt lgkmcnt(6)
	s_waitcnt vmcnt(19)
	v_pk_fma_f32 v[26:27], v[100:101], v[50:51], v[26:27] op_sel_hi:[1,0,1]
	v_pk_fma_f32 v[28:29], v[102:103], v[50:51], v[28:29] op_sel_hi:[1,0,1]
	v_pk_fma_f32 v[30:31], v[100:101], v[58:59], v[30:31] op_sel_hi:[1,0,1]
	v_pk_fma_f32 v[32:33], v[102:103], v[58:59], v[32:33] op_sel_hi:[1,0,1]
	v_pk_fma_f32 v[34:35], v[100:101], v[66:67], v[34:35] op_sel_hi:[1,0,1]
	v_pk_fma_f32 v[36:37], v[102:103], v[66:67], v[36:37] op_sel_hi:[1,0,1]
	global_load_dwordx4 v[100:103], v[180:181], off nt
	v_lshl_add_u64 v[180:181], s[40:41], 0, v[180:181]
	s_waitcnt vmcnt(19)
	v_pk_fma_f32 v[26:27], v[104:105], v[50:51], v[26:27] op_sel:[0,1,0]
	v_pk_fma_f32 v[28:29], v[106:107], v[50:51], v[28:29] op_sel:[0,1,0]
	v_pk_fma_f32 v[30:31], v[104:105], v[58:59], v[30:31] op_sel:[0,1,0]
	v_pk_fma_f32 v[32:33], v[106:107], v[58:59], v[32:33] op_sel:[0,1,0]
	v_pk_fma_f32 v[34:35], v[104:105], v[66:67], v[34:35] op_sel:[0,1,0]
	v_pk_fma_f32 v[36:37], v[106:107], v[66:67], v[36:37] op_sel:[0,1,0]
	global_load_dwordx4 v[104:107], v[180:181], off nt
	v_lshl_add_u64 v[180:181], s[40:41], 0, v[180:181]
	s_waitcnt vmcnt(19)
	v_pk_fma_f32 v[26:27], v[108:109], v[52:53], v[26:27] op_sel_hi:[1,0,1]
	v_pk_fma_f32 v[28:29], v[110:111], v[52:53], v[28:29] op_sel_hi:[1,0,1]
	v_pk_fma_f32 v[30:31], v[108:109], v[60:61], v[30:31] op_sel_hi:[1,0,1]
	v_pk_fma_f32 v[32:33], v[110:111], v[60:61], v[32:33] op_sel_hi:[1,0,1]
	v_pk_fma_f32 v[34:35], v[108:109], v[68:69], v[34:35] op_sel_hi:[1,0,1]
	v_pk_fma_f32 v[36:37], v[110:111], v[68:69], v[36:37] op_sel_hi:[1,0,1]
	global_load_dwordx4 v[108:111], v[180:181], off nt
	v_lshl_add_u64 v[180:181], s[40:41], 0, v[180:181]
	s_waitcnt vmcnt(19)
	v_pk_fma_f32 v[26:27], v[112:113], v[52:53], v[26:27] op_sel:[0,1,0]
	v_pk_fma_f32 v[28:29], v[114:115], v[52:53], v[28:29] op_sel:[0,1,0]
	v_pk_fma_f32 v[30:31], v[112:113], v[60:61], v[30:31] op_sel:[0,1,0]
	v_pk_fma_f32 v[32:33], v[114:115], v[60:61], v[32:33] op_sel:[0,1,0]
	v_pk_fma_f32 v[34:35], v[112:113], v[68:69], v[34:35] op_sel:[0,1,0]
	v_pk_fma_f32 v[36:37], v[114:115], v[68:69], v[36:37] op_sel:[0,1,0]
	global_load_dwordx4 v[112:115], v[180:181], off nt
	v_lshl_add_u64 v[180:181], s[40:41], 0, v[180:181]
	s_waitcnt vmcnt(19)
	v_pk_fma_f32 v[26:27], v[116:117], v[54:55], v[26:27] op_sel_hi:[1,0,1]
	v_pk_fma_f32 v[28:29], v[118:119], v[54:55], v[28:29] op_sel_hi:[1,0,1]
	v_pk_fma_f32 v[30:31], v[116:117], v[62:63], v[30:31] op_sel_hi:[1,0,1]
	v_pk_fma_f32 v[32:33], v[118:119], v[62:63], v[32:33] op_sel_hi:[1,0,1]
	v_pk_fma_f32 v[34:35], v[116:117], v[70:71], v[34:35] op_sel_hi:[1,0,1]
	v_pk_fma_f32 v[36:37], v[118:119], v[70:71], v[36:37] op_sel_hi:[1,0,1]
	s_waitcnt vmcnt(18)
	v_pk_fma_f32 v[26:27], v[120:121], v[54:55], v[26:27] op_sel:[0,1,0]
	v_pk_fma_f32 v[28:29], v[122:123], v[54:55], v[28:29] op_sel:[0,1,0]
	v_pk_fma_f32 v[30:31], v[120:121], v[62:63], v[30:31] op_sel:[0,1,0]
	v_pk_fma_f32 v[32:33], v[122:123], v[62:63], v[32:33] op_sel:[0,1,0]
	v_pk_fma_f32 v[34:35], v[120:121], v[70:71], v[34:35] op_sel:[0,1,0]
	v_pk_fma_f32 v[36:37], v[122:123], v[70:71], v[36:37] op_sel:[0,1,0]
	s_waitcnt vmcnt(17)
	v_pk_fma_f32 v[26:27], v[124:125], v[56:57], v[26:27] op_sel_hi:[1,0,1]
	v_pk_fma_f32 v[28:29], v[126:127], v[56:57], v[28:29] op_sel_hi:[1,0,1]
	v_pk_fma_f32 v[30:31], v[124:125], v[64:65], v[30:31] op_sel_hi:[1,0,1]
	v_pk_fma_f32 v[32:33], v[126:127], v[64:65], v[32:33] op_sel_hi:[1,0,1]
	v_pk_fma_f32 v[34:35], v[124:125], v[72:73], v[34:35] op_sel_hi:[1,0,1]
	v_pk_fma_f32 v[36:37], v[126:127], v[72:73], v[36:37] op_sel_hi:[1,0,1]
	s_waitcnt vmcnt(16)
	v_pk_fma_f32 v[26:27], v[128:129], v[56:57], v[26:27] op_sel:[0,1,0]
	v_pk_fma_f32 v[28:29], v[130:131], v[56:57], v[28:29] op_sel:[0,1,0]
	v_pk_fma_f32 v[30:31], v[128:129], v[64:65], v[30:31] op_sel:[0,1,0]
	v_pk_fma_f32 v[32:33], v[130:131], v[64:65], v[32:33] op_sel:[0,1,0]
	v_pk_fma_f32 v[34:35], v[128:129], v[72:73], v[34:35] op_sel:[0,1,0]
	v_pk_fma_f32 v[36:37], v[130:131], v[72:73], v[36:37] op_sel:[0,1,0]
	ds_read_b128 v[50:53], v46 offset:224
	ds_read_b128 v[54:57], v46 offset:240
	ds_read_b128 v[58:61], v46 offset:4320
	ds_read_b128 v[62:65], v46 offset:4336
	ds_read_b128 v[66:69], v46 offset:8416
	ds_read_b128 v[70:73], v46 offset:8432
	s_waitcnt lgkmcnt(6)
	s_waitcnt vmcnt(15)
	v_pk_fma_f32 v[26:27], v[132:133], v[2:3], v[26:27] op_sel_hi:[1,0,1]
	v_pk_fma_f32 v[28:29], v[134:135], v[2:3], v[28:29] op_sel_hi:[1,0,1]
	v_pk_fma_f32 v[30:31], v[132:133], v[10:11], v[30:31] op_sel_hi:[1,0,1]
	v_pk_fma_f32 v[32:33], v[134:135], v[10:11], v[32:33] op_sel_hi:[1,0,1]
	v_pk_fma_f32 v[34:35], v[132:133], v[18:19], v[34:35] op_sel_hi:[1,0,1]
	v_pk_fma_f32 v[36:37], v[134:135], v[18:19], v[36:37] op_sel_hi:[1,0,1]
	s_waitcnt vmcnt(14)
	v_pk_fma_f32 v[26:27], v[136:137], v[2:3], v[26:27] op_sel:[0,1,0]
	v_pk_fma_f32 v[28:29], v[138:139], v[2:3], v[28:29] op_sel:[0,1,0]
	v_pk_fma_f32 v[30:31], v[136:137], v[10:11], v[30:31] op_sel:[0,1,0]
	v_pk_fma_f32 v[32:33], v[138:139], v[10:11], v[32:33] op_sel:[0,1,0]
	v_pk_fma_f32 v[34:35], v[136:137], v[18:19], v[34:35] op_sel:[0,1,0]
	v_pk_fma_f32 v[36:37], v[138:139], v[18:19], v[36:37] op_sel:[0,1,0]
	s_waitcnt vmcnt(13)
	v_pk_fma_f32 v[26:27], v[140:141], v[4:5], v[26:27] op_sel_hi:[1,0,1]
	v_pk_fma_f32 v[28:29], v[142:143], v[4:5], v[28:29] op_sel_hi:[1,0,1]
	v_pk_fma_f32 v[30:31], v[140:141], v[12:13], v[30:31] op_sel_hi:[1,0,1]
	v_pk_fma_f32 v[32:33], v[142:143], v[12:13], v[32:33] op_sel_hi:[1,0,1]
	v_pk_fma_f32 v[34:35], v[140:141], v[20:21], v[34:35] op_sel_hi:[1,0,1]
	v_pk_fma_f32 v[36:37], v[142:143], v[20:21], v[36:37] op_sel_hi:[1,0,1]
	s_waitcnt vmcnt(12)
	v_pk_fma_f32 v[26:27], v[144:145], v[4:5], v[26:27] op_sel:[0,1,0]
	v_pk_fma_f32 v[28:29], v[146:147], v[4:5], v[28:29] op_sel:[0,1,0]
	v_pk_fma_f32 v[30:31], v[144:145], v[12:13], v[30:31] op_sel:[0,1,0]
	v_pk_fma_f32 v[32:33], v[146:147], v[12:13], v[32:33] op_sel:[0,1,0]
	v_pk_fma_f32 v[34:35], v[144:145], v[20:21], v[34:35] op_sel:[0,1,0]
	v_pk_fma_f32 v[36:37], v[146:147], v[20:21], v[36:37] op_sel:[0,1,0]
	s_waitcnt vmcnt(11)
	v_pk_fma_f32 v[26:27], v[148:149], v[6:7], v[26:27] op_sel_hi:[1,0,1]
	v_pk_fma_f32 v[28:29], v[150:151], v[6:7], v[28:29] op_sel_hi:[1,0,1]
	v_pk_fma_f32 v[30:31], v[148:149], v[14:15], v[30:31] op_sel_hi:[1,0,1]
	v_pk_fma_f32 v[32:33], v[150:151], v[14:15], v[32:33] op_sel_hi:[1,0,1]
	v_pk_fma_f32 v[34:35], v[148:149], v[22:23], v[34:35] op_sel_hi:[1,0,1]
	v_pk_fma_f32 v[36:37], v[150:151], v[22:23], v[36:37] op_sel_hi:[1,0,1]
	s_waitcnt vmcnt(10)
	v_pk_fma_f32 v[26:27], v[152:153], v[6:7], v[26:27] op_sel:[0,1,0]
	v_pk_fma_f32 v[28:29], v[154:155], v[6:7], v[28:29] op_sel:[0,1,0]
	v_pk_fma_f32 v[30:31], v[152:153], v[14:15], v[30:31] op_sel:[0,1,0]
	v_pk_fma_f32 v[32:33], v[154:155], v[14:15], v[32:33] op_sel:[0,1,0]
	v_pk_fma_f32 v[34:35], v[152:153], v[22:23], v[34:35] op_sel:[0,1,0]
	v_pk_fma_f32 v[36:37], v[154:155], v[22:23], v[36:37] op_sel:[0,1,0]
	s_waitcnt vmcnt(9)
	v_pk_fma_f32 v[26:27], v[156:157], v[8:9], v[26:27] op_sel_hi:[1,0,1]
	v_pk_fma_f32 v[28:29], v[158:159], v[8:9], v[28:29] op_sel_hi:[1,0,1]
	v_pk_fma_f32 v[30:31], v[156:157], v[16:17], v[30:31] op_sel_hi:[1,0,1]
	v_pk_fma_f32 v[32:33], v[158:159], v[16:17], v[32:33] op_sel_hi:[1,0,1]
	v_pk_fma_f32 v[34:35], v[156:157], v[24:25], v[34:35] op_sel_hi:[1,0,1]
	v_pk_fma_f32 v[36:37], v[158:159], v[24:25], v[36:37] op_sel_hi:[1,0,1]
	s_waitcnt vmcnt(8)
	v_pk_fma_f32 v[26:27], v[160:161], v[8:9], v[26:27] op_sel:[0,1,0]
	v_pk_fma_f32 v[28:29], v[162:163], v[8:9], v[28:29] op_sel:[0,1,0]
	v_pk_fma_f32 v[30:31], v[160:161], v[16:17], v[30:31] op_sel:[0,1,0]
	v_pk_fma_f32 v[32:33], v[162:163], v[16:17], v[32:33] op_sel:[0,1,0]
	v_pk_fma_f32 v[34:35], v[160:161], v[24:25], v[34:35] op_sel:[0,1,0]
	v_pk_fma_f32 v[36:37], v[162:163], v[24:25], v[36:37] op_sel:[0,1,0]
	s_waitcnt lgkmcnt(0)
	s_waitcnt vmcnt(7)
	v_pk_fma_f32 v[26:27], v[164:165], v[50:51], v[26:27] op_sel_hi:[1,0,1]
	v_pk_fma_f32 v[28:29], v[166:167], v[50:51], v[28:29] op_sel_hi:[1,0,1]
	v_pk_fma_f32 v[30:31], v[164:165], v[58:59], v[30:31] op_sel_hi:[1,0,1]
	v_pk_fma_f32 v[32:33], v[166:167], v[58:59], v[32:33] op_sel_hi:[1,0,1]
	v_pk_fma_f32 v[34:35], v[164:165], v[66:67], v[34:35] op_sel_hi:[1,0,1]
	v_pk_fma_f32 v[36:37], v[166:167], v[66:67], v[36:37] op_sel_hi:[1,0,1]
	s_waitcnt vmcnt(6)
	v_pk_fma_f32 v[26:27], v[168:169], v[50:51], v[26:27] op_sel:[0,1,0]
	v_pk_fma_f32 v[28:29], v[170:171], v[50:51], v[28:29] op_sel:[0,1,0]
	v_pk_fma_f32 v[30:31], v[168:169], v[58:59], v[30:31] op_sel:[0,1,0]
	v_pk_fma_f32 v[32:33], v[170:171], v[58:59], v[32:33] op_sel:[0,1,0]
	v_pk_fma_f32 v[34:35], v[168:169], v[66:67], v[34:35] op_sel:[0,1,0]
	v_pk_fma_f32 v[36:37], v[170:171], v[66:67], v[36:37] op_sel:[0,1,0]
	s_waitcnt vmcnt(5)
	v_pk_fma_f32 v[26:27], v[172:173], v[52:53], v[26:27] op_sel_hi:[1,0,1]
	v_pk_fma_f32 v[28:29], v[174:175], v[52:53], v[28:29] op_sel_hi:[1,0,1]
	v_pk_fma_f32 v[30:31], v[172:173], v[60:61], v[30:31] op_sel_hi:[1,0,1]
	v_pk_fma_f32 v[32:33], v[174:175], v[60:61], v[32:33] op_sel_hi:[1,0,1]
	v_pk_fma_f32 v[34:35], v[172:173], v[68:69], v[34:35] op_sel_hi:[1,0,1]
	v_pk_fma_f32 v[36:37], v[174:175], v[68:69], v[36:37] op_sel_hi:[1,0,1]
	s_waitcnt vmcnt(4)
	v_pk_fma_f32 v[26:27], v[176:177], v[52:53], v[26:27] op_sel:[0,1,0]
	v_pk_fma_f32 v[28:29], v[178:179], v[52:53], v[28:29] op_sel:[0,1,0]
	v_pk_fma_f32 v[30:31], v[176:177], v[60:61], v[30:31] op_sel:[0,1,0]
	v_pk_fma_f32 v[32:33], v[178:179], v[60:61], v[32:33] op_sel:[0,1,0]
	v_pk_fma_f32 v[34:35], v[176:177], v[68:69], v[34:35] op_sel:[0,1,0]
	v_pk_fma_f32 v[36:37], v[178:179], v[68:69], v[36:37] op_sel:[0,1,0]
	s_waitcnt vmcnt(3)
	v_pk_fma_f32 v[26:27], v[100:101], v[54:55], v[26:27] op_sel_hi:[1,0,1]
	v_pk_fma_f32 v[28:29], v[102:103], v[54:55], v[28:29] op_sel_hi:[1,0,1]
	v_pk_fma_f32 v[30:31], v[100:101], v[62:63], v[30:31] op_sel_hi:[1,0,1]
	v_pk_fma_f32 v[32:33], v[102:103], v[62:63], v[32:33] op_sel_hi:[1,0,1]
	v_pk_fma_f32 v[34:35], v[100:101], v[70:71], v[34:35] op_sel_hi:[1,0,1]
	v_pk_fma_f32 v[36:37], v[102:103], v[70:71], v[36:37] op_sel_hi:[1,0,1]
	s_waitcnt vmcnt(2)
	v_pk_fma_f32 v[26:27], v[104:105], v[54:55], v[26:27] op_sel:[0,1,0]
	v_pk_fma_f32 v[28:29], v[106:107], v[54:55], v[28:29] op_sel:[0,1,0]
	v_pk_fma_f32 v[30:31], v[104:105], v[62:63], v[30:31] op_sel:[0,1,0]
	v_pk_fma_f32 v[32:33], v[106:107], v[62:63], v[32:33] op_sel:[0,1,0]
	v_pk_fma_f32 v[34:35], v[104:105], v[70:71], v[34:35] op_sel:[0,1,0]
	v_pk_fma_f32 v[36:37], v[106:107], v[70:71], v[36:37] op_sel:[0,1,0]
	s_waitcnt vmcnt(1)
	v_pk_fma_f32 v[26:27], v[108:109], v[56:57], v[26:27] op_sel_hi:[1,0,1]
	v_pk_fma_f32 v[28:29], v[110:111], v[56:57], v[28:29] op_sel_hi:[1,0,1]
	v_pk_fma_f32 v[30:31], v[108:109], v[64:65], v[30:31] op_sel_hi:[1,0,1]
	v_pk_fma_f32 v[32:33], v[110:111], v[64:65], v[32:33] op_sel_hi:[1,0,1]
	v_pk_fma_f32 v[34:35], v[108:109], v[72:73], v[34:35] op_sel_hi:[1,0,1]
	v_pk_fma_f32 v[36:37], v[110:111], v[72:73], v[36:37] op_sel_hi:[1,0,1]
	s_waitcnt vmcnt(0)
	v_pk_fma_f32 v[26:27], v[112:113], v[56:57], v[26:27] op_sel:[0,1,0]
	v_pk_fma_f32 v[28:29], v[114:115], v[56:57], v[28:29] op_sel:[0,1,0]
	v_pk_fma_f32 v[30:31], v[112:113], v[64:65], v[30:31] op_sel:[0,1,0]
	v_pk_fma_f32 v[32:33], v[114:115], v[64:65], v[32:33] op_sel:[0,1,0]
	v_pk_fma_f32 v[34:35], v[112:113], v[72:73], v[34:35] op_sel:[0,1,0]
	v_pk_fma_f32 v[36:37], v[114:115], v[72:73], v[36:37] op_sel:[0,1,0]
	s_nop 0
	s_nop 0
	s_nop 0
	s_nop 0
	s_nop 0
	s_nop 0
	s_nop 0
	s_nop 0
	s_nop 0
	s_nop 0
	s_nop 0
	s_nop 0
	s_nop 0
	ds_write_b128 v40, v[26:29] offset:12288
	ds_write_b128 v40, v[30:33] offset:12800
	ds_write_b128 v40, v[34:37] offset:13312
	s_waitcnt lgkmcnt(0)
	s_barrier
	s_and_saveexec_b64 s[6:7], vcc
	s_cbranch_execz .LBB0_958
	s_load_dwordx2 s[8:9], s[48:49], 0x50
	s_mul_i32 s10, s4, 0x1800
	s_ashr_i32 s11, s10, 31
	s_lshl_b64 s[10:11], s[10:11], 2
	s_waitcnt lgkmcnt(0)
	s_add_u32 s5, s8, s10
	s_addc_u32 s9, s9, s11
	s_add_u32 s8, s5, s0
	s_addc_u32 s9, s9, s1
	global_load_dwordx4 v[2:5], v0, s[8:9]
	ds_read_b128 v[6:9], v41 offset:12288
	ds_read_b128 v[10:13], v41 offset:13824
	ds_read_b128 v[14:17], v41 offset:15360
	ds_read_b128 v[18:21], v41 offset:16896
	ds_read_b128 v[22:25], v41 offset:18432
	ds_read_b128 v[26:29], v41 offset:19968
	ds_read_b128 v[30:33], v41 offset:21504
	ds_read_b128 v[34:37], v41 offset:23040
	ds_read_b128 v[44:47], v41 offset:24576
	ds_read_b128 v[48:51], v41 offset:26112
	ds_read_b128 v[52:55], v41 offset:27648
	ds_read_b128 v[56:59], v41 offset:29184
	s_waitcnt vmcnt(0) lgkmcnt(11)
	v_pk_add_f32 v[60:61], v[4:5], v[8:9]
	v_pk_add_f32 v[62:63], v[2:3], v[6:7]
	s_waitcnt lgkmcnt(10)
	v_pk_add_f32 v[12:13], v[60:61], v[12:13]
	v_pk_add_f32 v[10:11], v[62:63], v[10:11]
	s_waitcnt lgkmcnt(9)
	v_pk_add_f32 v[60:61], v[12:13], v[16:17]
	v_pk_add_f32 v[62:63], v[10:11], v[14:15]
	s_waitcnt lgkmcnt(8)
	v_pk_add_f32 v[20:21], v[60:61], v[20:21]
	v_pk_add_f32 v[18:19], v[62:63], v[18:19]
	s_waitcnt lgkmcnt(7)
	v_pk_add_f32 v[20:21], v[20:21], v[24:25]
	v_pk_add_f32 v[18:19], v[18:19], v[22:23]
	s_waitcnt lgkmcnt(6)
	v_pk_add_f32 v[20:21], v[20:21], v[28:29]
	v_pk_add_f32 v[18:19], v[18:19], v[26:27]
	s_waitcnt lgkmcnt(5)
	v_pk_add_f32 v[20:21], v[20:21], v[32:33]
	v_pk_add_f32 v[18:19], v[18:19], v[30:31]
	ds_read_b128 v[2:5], v41 offset:30720
	ds_read_b128 v[6:9], v41 offset:32256
	ds_read_b128 v[10:13], v41 offset:33792
	ds_read_b128 v[14:17], v41 offset:35328
	s_load_dwordx4 s[8:11], s[48:49], 0x140
	s_waitcnt lgkmcnt(0)
	v_pk_add_f32 v[20:21], v[20:21], v[36:37]
	v_pk_add_f32 v[18:19], v[18:19], v[34:35]
	v_pk_add_f32 v[20:21], v[20:21], v[46:47]
	v_pk_add_f32 v[18:19], v[18:19], v[44:45]
	v_pk_add_f32 v[20:21], v[20:21], v[50:51]
	v_pk_add_f32 v[18:19], v[18:19], v[48:49]
	v_pk_add_f32 v[20:21], v[20:21], v[54:55]
	v_pk_add_f32 v[18:19], v[18:19], v[52:53]
	v_pk_add_f32 v[20:21], v[20:21], v[58:59]
	v_pk_add_f32 v[18:19], v[18:19], v[56:57]
	v_mad_u64_u32 v[60:61], s[4:5], s4, 3, v[38:39]
	v_mov_b64_e32 v[62:63], s[10:11]
	v_pk_add_f32 v[4:5], v[20:21], v[4:5]
	v_pk_add_f32 v[2:3], v[18:19], v[2:3]
	v_mad_i64_i32 v[60:61], s[4:5], v60, s13, v[62:63]
	v_pk_add_f32 v[4:5], v[4:5], v[8:9]
	v_pk_add_f32 v[2:3], v[2:3], v[6:7]
	v_lshl_add_u64 v[60:61], v[60:61], 0, s[0:1]
	v_pk_add_f32 v[4:5], v[4:5], v[12:13]
	v_pk_add_f32 v[2:3], v[2:3], v[10:11]
	v_pk_add_f32 v[4:5], v[4:5], v[16:17]
	v_pk_add_f32 v[2:3], v[2:3], v[14:15]
	v_lshl_add_u64 v[6:7], v[60:61], 0, v[0:1]
	global_store_dwordx4 v[6:7], v[2:5], off
	s_branch .LBB0_958
